# GDN gated-RMSNorm pass (old phase 5) executed by the scan workgroups inside phase 4; phase 5 and its grid barrier removed
# speedup vs baseline: 1.0223x; 1.0009x over previous
.LBB0_1137:
	v_readlane_b32 s0, v252, 55
	v_readlane_b32 s1, v252, 56
	s_and_b64 vcc, exec, s[0:1]
	s_cbranch_vccz .Lmy_m3_skip
	s_waitcnt vmcnt(0) lgkmcnt(0)
	s_barrier
	s_mul_hi_u32 s0, s42, 0x2aaaaaab
	s_mul_i32 s1, s0, 6
	s_sub_i32 s1, s42, s1
	s_lshr_b32 s2, s47, 6
	s_mul_i32 s2, s2, 6
	s_mul_i32 s26, s0, 0x300
	s_add_i32 s26, s26, s2
	s_add_i32 s26, s26, s1
	s_mul_i32 s23, s0, 0x300
	s_addk_i32 s23, 0x300
	v_readlane_b32 s8, v252, 63
	v_readlane_b32 s9, v253, 0
	s_mov_b64 s[2:3], s[54:55]
	s_mov_b64 s[4:5], s[54:55]
	s_mov_b64 s[6:7], s[54:55]
	s_mov_b64 s[0:1], s[44:45]
	s_andn2_b64 vcc, exec, s[8:9]
	s_mov_b32 s14, 0x8000
	s_movk_i32 s15, 0x6000
	s_movk_i32 s16, 0x4000
	s_mov_b32 s17, 0xc000
	s_movk_i32 s18, 0x7fff
	s_mov_b32 s19, 0xffff0000
	s_movk_i32 s20, 0x2000
	s_mov_b32 s21, 0xf800000
	s_mov_b32 s22, 0xe801000
	s_mov_b64 s[24:25], 0xc00
	v_mbcnt_lo_u32_b32 v0, -1, 0
	v_mbcnt_hi_u32_b32 v0, -1, v0
	v_lshlrev_b32_e32 v6, 1, v0
	v_ashrrev_i32_e32 v7, 31, v6
	v_lshlrev_b64 v[0:1], 1, v[6:7]
	v_lshl_add_u64 v[2:3], s[4:5], 0, v[0:1]
	s_mov_b64 s[4:5], 0x33800000
	v_lshl_add_u64 v[2:3], v[2:3], 0, s[4:5]
	v_lshl_add_u64 v[4:5], s[6:7], 0, v[0:1]
	s_mov_b64 s[4:5], 0x6800000
	s_load_dwordx2 s[0:1], s[0:1], 0x38
	v_lshl_add_u64 v[4:5], v[4:5], 0, s[4:5]
	v_readlane_b32 s4, v251, 39
	v_readlane_b32 s5, v251, 40
	s_mov_b32 s6, s4
	s_ashr_i32 s7, s4, 31
	v_writelane_b32 v251, s4, 39
	s_mov_b32 s8, s26
	s_nop 0
	v_writelane_b32 v251, s5, 40
	s_lshl_b64 s[4:5], s[6:7], 9
	s_waitcnt lgkmcnt(0)
	s_add_u32 s0, s0, s4
	s_addc_u32 s1, s1, s5
	v_lshl_add_u64 v[6:7], v[6:7], 2, s[0:1]
	global_load_dwordx2 v[6:7], v[6:7], off
	s_lshl_b32 s6, s26, 7
	s_movk_i32 s7, 0x1800
.Lmy_m3_loop:
	s_mul_hi_i32 s0, s8, 0x2aaaaaab
	s_lshr_b32 s1, s0, 31
	s_add_i32 s4, s0, s1
	s_mul_i32 s0, s4, 0xfffffd00
	s_add_i32 s0, s6, s0
	s_ashr_i32 s1, s0, 31
	s_lshl_b64 s[0:1], s[0:1], 1
	v_lshl_add_u64 v[8:9], v[2:3], 0, s[0:1]
	v_mov_b32_e32 v10, 0x6000
	v_mad_i64_i32 v[10:11], s[12:13], s4, v10, v[8:9]
	global_load_dword v31, v[10:11], off
	s_ashr_i32 s5, s4, 31
	s_lshl_b64 s[10:11], s[4:5], 4
	s_mul_i32 s12, s4, 0x38000
	s_mul_hi_i32 s9, s4, 0x38000
	s_add_u32 s12, s2, s12
	s_addc_u32 s9, s3, s9
	s_add_u32 s12, s12, s0
	s_addc_u32 s13, s9, s1
	v_lshl_add_u64 v[10:11], s[12:13], 0, v[0:1]
	v_add_co_u32_e32 v10, vcc, s22, v10
	s_or_b32 s9, s10, 1
	s_nop 0
	v_addc_co_u32_e32 v11, vcc, 0, v11, vcc
	global_load_dword v34, v[10:11], off offset:512
	v_mov_b32_e32 v10, 0x600
	v_mad_u64_u32 v[8:9], s[12:13], s9, v10, v[8:9]
	s_mul_i32 s10, s11, 0x600
	v_add_u32_e32 v9, s10, v9
	s_mul_i32 s10, s11, 0x3800
	s_mul_hi_u32 s11, s9, 0x3800
	s_add_i32 s11, s11, s10
	s_mulk_i32 s9, 0x3800
	s_add_u32 s9, s2, s9
	s_addc_u32 s11, s3, s11
	s_add_u32 s10, s9, s0
	s_addc_u32 s11, s11, s1
	v_lshl_add_u64 v[32:33], s[10:11], 0, v[0:1]
	v_add_co_u32_e32 v10, vcc, s22, v32
	s_mov_b32 s9, 0xe804000
	s_nop 0
	v_addc_co_u32_e32 v11, vcc, 0, v33, vcc
	v_add_co_u32_e32 v12, vcc, s9, v32
	s_mov_b64 s[10:11], 0x600
	s_nop 0
	v_addc_co_u32_e32 v13, vcc, 0, v33, vcc
	s_mov_b32 s9, 0xe808000
	global_load_dword v35, v[8:9], off
	global_load_dword v37, v[8:9], off offset:1536
	global_load_dword v39, v[8:9], off offset:3072
	global_load_dword v36, v[10:11], off offset:512
	global_load_dword v38, v[12:13], off offset:2560
	v_lshl_add_u64 v[10:11], v[8:9], 0, s[10:11]
	v_lshl_add_u64 v[12:13], v[8:9], 0, s[24:25]
	v_add_co_u32_e32 v8, vcc, s9, v32
	s_mov_b32 s9, 0xe80b000
	s_nop 0
	v_addc_co_u32_e32 v9, vcc, 0, v33, vcc
	global_load_dword v40, v[8:9], off offset:512
	v_lshl_add_u64 v[8:9], v[10:11], 0, s[24:25]
	global_load_dword v41, v[10:11], off offset:3072
	global_load_dword v43, v[12:13], off offset:3072
	v_add_co_u32_e32 v10, vcc, s9, v32
	s_mov_b32 s9, 0xe80f000
	s_nop 0
	v_addc_co_u32_e32 v11, vcc, 0, v33, vcc
	global_load_dword v42, v[10:11], off offset:2560
	v_lshl_add_u64 v[10:11], v[12:13], 0, s[24:25]
	v_add_co_u32_e32 v12, vcc, s9, v32
	s_mov_b32 s9, 0xe812000
	s_nop 0
	v_addc_co_u32_e32 v13, vcc, 0, v33, vcc
	global_load_dword v30, v[12:13], off offset:512
	v_lshl_add_u64 v[12:13], v[8:9], 0, s[24:25]
	global_load_dword v29, v[8:9], off offset:3072
	v_add_co_u32_e32 v8, vcc, s9, v32
	s_mov_b32 s9, 0xe816000
	s_nop 0
	v_addc_co_u32_e32 v9, vcc, 0, v33, vcc
	global_load_dword v28, v[8:9], off offset:2560
	v_lshl_add_u64 v[8:9], v[10:11], 0, s[24:25]
	global_load_dword v27, v[10:11], off offset:3072
	v_add_co_u32_e32 v10, vcc, s9, v32
	s_mov_b32 s9, 0xe819000
	s_nop 0
	v_addc_co_u32_e32 v11, vcc, 0, v33, vcc
	global_load_dword v26, v[10:11], off offset:512
	v_lshl_add_u64 v[10:11], v[12:13], 0, s[24:25]
	global_load_dword v25, v[12:13], off offset:3072
	v_add_co_u32_e32 v12, vcc, s9, v32
	s_mov_b32 s9, 0xe81d000
	s_nop 0
	v_addc_co_u32_e32 v13, vcc, 0, v33, vcc
	global_load_dword v24, v[12:13], off offset:2560
	v_lshl_add_u64 v[12:13], v[8:9], 0, s[24:25]
	global_load_dword v23, v[8:9], off offset:3072
	v_add_co_u32_e32 v8, vcc, s9, v32
	s_mov_b32 s9, 0xe820000
	s_nop 0
	v_addc_co_u32_e32 v9, vcc, 0, v33, vcc
	global_load_dword v22, v[8:9], off offset:512
	v_lshl_add_u64 v[8:9], v[10:11], 0, s[24:25]
	global_load_dword v21, v[10:11], off offset:3072
	v_add_co_u32_e32 v10, vcc, s9, v32
	s_mov_b32 s9, 0xe824000
	s_nop 0
	v_addc_co_u32_e32 v11, vcc, 0, v33, vcc
	global_load_dword v20, v[10:11], off offset:2560
	v_lshl_add_u64 v[10:11], v[12:13], 0, s[24:25]
	global_load_dword v19, v[12:13], off offset:3072
	v_add_co_u32_e32 v12, vcc, s9, v32
	s_mov_b32 s9, 0xe827000
	s_nop 0
	v_addc_co_u32_e32 v13, vcc, 0, v33, vcc
	global_load_dword v18, v[12:13], off offset:512
	v_lshl_add_u64 v[12:13], v[8:9], 0, s[24:25]
	global_load_dword v17, v[8:9], off offset:3072
	v_add_co_u32_e32 v8, vcc, s9, v32
	s_mov_b32 s9, 0xe82b000
	s_nop 0
	v_addc_co_u32_e32 v9, vcc, 0, v33, vcc
	global_load_dword v16, v[8:9], off offset:2560
	v_lshl_add_u64 v[8:9], v[10:11], 0, s[24:25]
	global_load_dword v15, v[10:11], off offset:3072
	v_add_co_u32_e32 v10, vcc, s9, v32
	s_mov_b32 s9, 0xe82e000
	s_nop 0
	v_addc_co_u32_e32 v11, vcc, 0, v33, vcc
	global_load_dword v14, v[10:11], off offset:512
	s_nop 0
	global_load_dword v13, v[12:13], off offset:3072
	v_add_co_u32_e32 v10, vcc, s9, v32
	s_mov_b32 s9, 0xe832000
	s_nop 0
	v_addc_co_u32_e32 v11, vcc, 0, v33, vcc
	global_load_dword v12, v[10:11], off offset:2560
	s_nop 0
	global_load_dword v11, v[8:9], off offset:3072
	v_add_co_u32_e32 v8, vcc, s9, v32
	s_waitcnt vmcnt(30)
	v_lshlrev_b32_e32 v32, 16, v31
	v_and_b32_e32 v31, 0xffff0000, v31
	v_addc_co_u32_e32 v9, vcc, 0, v33, vcc
	v_mul_f32_e32 v33, v31, v31
	v_fmac_f32_e32 v33, v32, v32
	global_load_dword v10, v[8:9], off offset:512
	v_lshl_add_u64 v[8:9], v[4:5], 0, s[0:1]
	v_add_f32_dpp v33, v33, v33 quad_perm:[1,0,3,2] row_mask:0xf bank_mask:0xf bound_ctrl:1
	s_add_i32 s8, s8, 48
	s_add_i32 s6, s6, s7
	v_add_f32_dpp v33, v33, v33 quad_perm:[2,3,0,1] row_mask:0xf bank_mask:0xf bound_ctrl:1
	s_nop 1
	v_add_f32_dpp v33, v33, v33 row_half_mirror row_mask:0xf bank_mask:0xf bound_ctrl:1
	s_nop 1
	v_add_f32_dpp v33, v33, v33 row_mirror row_mask:0xf bank_mask:0xf bound_ctrl:1
	ds_swizzle_b32 v44, v33 offset:swizzle(SWAP,16)
	s_waitcnt lgkmcnt(0)
	v_add_f32_e32 v33, v33, v44
	v_mov_b32_e32 v44, v33
	s_nop 1
	v_permlane32_swap_b32_e32 v33, v44
	v_add_f32_e32 v33, v33, v44
	v_fmamk_f32 v33, v33, 0x3c000000, v206
	v_cmp_gt_f32_e32 vcc, s21, v33
	v_mul_f32_e32 v44, 0x4f800000, v33
	s_nop 0
	v_cndmask_b32_e32 v33, v33, v44, vcc
	v_sqrt_f32_e32 v44, v33
	s_nop 0
	v_add_u32_e32 v45, -1, v44
	v_fma_f32 v46, -v45, v44, v33
	v_cmp_ge_f32_e64 s[0:1], 0, v46
	v_add_u32_e32 v46, 1, v44
	s_nop 0
	v_cndmask_b32_e64 v45, v44, v45, s[0:1]
	v_fma_f32 v44, -v46, v44, v33
	v_cmp_lt_f32_e64 s[0:1], 0, v44
	s_nop 1
	v_cndmask_b32_e64 v44, v45, v46, s[0:1]
	v_mul_f32_e32 v45, 0x37800000, v44
	v_cndmask_b32_e32 v44, v44, v45, vcc
	v_cmp_class_f32_e32 vcc, v33, v207
	s_nop 1
	v_cndmask_b32_e32 v33, v44, v33, vcc
	v_div_scale_f32 v44, s[0:1], v33, v33, 1.0
	v_rcp_f32_e32 v45, v44
	s_lshl_b64 s[0:1], s[4:5], 16
	v_lshl_add_u64 v[8:9], v[8:9], 0, s[0:1]
	s_cmp_lt_i32 s8, s23
	v_fma_f32 v46, -v44, v45, 1.0
	v_fmac_f32_e32 v45, v46, v45
	v_div_scale_f32 v46, vcc, 1.0, v33, 1.0
	v_mul_f32_e32 v47, v46, v45
	v_fma_f32 v48, -v44, v47, v46
	v_fmac_f32_e32 v47, v48, v45
	v_fma_f32 v44, -v44, v47, v46
	v_div_fmas_f32 v44, v44, v45, v47
	v_div_fixup_f32 v33, v44, v33, 1.0
	s_waitcnt vmcnt(30)
	v_lshlrev_b32_e32 v44, 16, v34
	v_mul_f32_e32 v32, v33, v32
	v_mul_f32_e32 v45, 0xbfb8aa3b, v44
	v_mul_f32_e32 v31, v33, v31
	v_and_b32_e32 v33, 0xffff0000, v34
	v_exp_f32_e32 v45, v45
	v_mul_f32_e32 v34, 0xbfb8aa3b, v33
	v_exp_f32_e32 v34, v34
	v_mul_f32_e32 v32, v6, v32
	v_add_f32_e32 v45, 1.0, v45
	v_rcp_f32_e32 v45, v45
	v_add_f32_e32 v34, 1.0, v34
	v_rcp_f32_e32 v34, v34
	v_mul_f32_e32 v31, v7, v31
	v_mul_f32_e32 v44, v45, v44
	v_mul_f32_e32 v32, v44, v32
	v_mul_f32_e32 v33, v34, v33
	v_mul_f32_e32 v31, v33, v31
	v_bfe_u32 v33, v32, 16, 1
	v_add3_u32 v32, v32, v33, s18
	v_bfe_u32 v33, v31, 16, 1
	v_lshrrev_b32_e32 v32, 16, v32
	v_add3_u32 v31, v31, v33, s18
	v_and_or_b32 v31, v31, s19, v32
	s_waitcnt vmcnt(29)
	v_and_b32_e32 v32, 0xffff0000, v35
	global_store_dword v[8:9], v31, off
	v_lshlrev_b32_e32 v31, 16, v35
	v_mul_f32_e32 v33, v32, v32
	v_fmac_f32_e32 v33, v31, v31
	s_nop 1
	v_add_f32_dpp v33, v33, v33 quad_perm:[1,0,3,2] row_mask:0xf bank_mask:0xf bound_ctrl:1
	s_nop 1
	v_add_f32_dpp v33, v33, v33 quad_perm:[2,3,0,1] row_mask:0xf bank_mask:0xf bound_ctrl:1
	s_nop 1
	v_add_f32_dpp v33, v33, v33 row_half_mirror row_mask:0xf bank_mask:0xf bound_ctrl:1
	s_nop 1
	v_add_f32_dpp v33, v33, v33 row_mirror row_mask:0xf bank_mask:0xf bound_ctrl:1
	ds_swizzle_b32 v34, v33 offset:swizzle(SWAP,16)
	s_waitcnt lgkmcnt(0)
	v_add_f32_e32 v33, v33, v34
	v_mov_b32_e32 v34, v33
	s_nop 1
	v_permlane32_swap_b32_e32 v33, v34
	v_add_f32_e32 v33, v33, v34
	v_fmamk_f32 v33, v33, 0x3c000000, v206
	v_cmp_gt_f32_e32 vcc, s21, v33
	v_mul_f32_e32 v34, 0x4f800000, v33
	s_nop 0
	v_cndmask_b32_e32 v33, v33, v34, vcc
	v_sqrt_f32_e32 v34, v33
	s_nop 0
	v_add_u32_e32 v35, -1, v34
	v_fma_f32 v44, -v35, v34, v33
	v_cmp_ge_f32_e64 s[0:1], 0, v44
	v_add_u32_e32 v44, 1, v34
	s_nop 0
	v_cndmask_b32_e64 v35, v34, v35, s[0:1]
	v_fma_f32 v34, -v44, v34, v33
	v_cmp_lt_f32_e64 s[0:1], 0, v34
	s_nop 1
	v_cndmask_b32_e64 v34, v35, v44, s[0:1]
	v_mul_f32_e32 v35, 0x37800000, v34
	v_cndmask_b32_e32 v34, v34, v35, vcc
	v_cmp_class_f32_e32 vcc, v33, v207
	s_nop 1
	v_cndmask_b32_e32 v33, v34, v33, vcc
	v_div_scale_f32 v34, s[0:1], v33, v33, 1.0
	v_rcp_f32_e32 v35, v34
	s_nop 0
	v_fma_f32 v44, -v34, v35, 1.0
	v_fmac_f32_e32 v35, v44, v35
	v_div_scale_f32 v44, vcc, 1.0, v33, 1.0
	v_mul_f32_e32 v45, v44, v35
	v_fma_f32 v46, -v34, v45, v44
	v_fmac_f32_e32 v45, v46, v35
	v_fma_f32 v34, -v34, v45, v44
	v_div_fmas_f32 v34, v34, v35, v45
	v_div_fixup_f32 v33, v34, v33, 1.0
	s_waitcnt vmcnt(27)
	v_lshlrev_b32_e32 v34, 16, v36
	v_mul_f32_e32 v35, 0xbfb8aa3b, v34
	v_exp_f32_e32 v35, v35
	v_mul_f32_e32 v31, v33, v31
	v_mul_f32_e32 v31, v6, v31
	v_mul_f32_e32 v32, v33, v32
	v_add_f32_e32 v35, 1.0, v35
	v_rcp_f32_e32 v35, v35
	v_and_b32_e32 v33, 0xffff0000, v36
	v_mul_f32_e32 v32, v7, v32
	v_mul_f32_e32 v34, v35, v34
	v_mul_f32_e32 v31, v34, v31
	v_mul_f32_e32 v34, 0xbfb8aa3b, v33
	v_exp_f32_e32 v34, v34
	s_nop 0
	v_add_f32_e32 v34, 1.0, v34
	v_rcp_f32_e32 v34, v34
	s_nop 0
	v_mul_f32_e32 v33, v34, v33
	v_mul_f32_e32 v32, v33, v32
	v_bfe_u32 v33, v31, 16, 1
	v_add3_u32 v31, v31, v33, s18
	v_bfe_u32 v33, v32, 16, 1
	v_lshrrev_b32_e32 v31, 16, v31
	v_add3_u32 v32, v32, v33, s18
	v_and_or_b32 v31, v32, s19, v31
	v_add_co_u32_e32 v32, vcc, s20, v8
	v_and_b32_e32 v34, 0xffff0000, v37
	s_nop 0
	v_addc_co_u32_e32 v33, vcc, 0, v9, vcc
	global_store_dword v[32:33], v31, off offset:-4096
	v_lshlrev_b32_e32 v31, 16, v37
	v_mul_f32_e32 v35, v34, v34
	v_fmac_f32_e32 v35, v31, v31
	s_nop 1
	v_add_f32_dpp v35, v35, v35 quad_perm:[1,0,3,2] row_mask:0xf bank_mask:0xf bound_ctrl:1
	s_nop 1
	v_add_f32_dpp v35, v35, v35 quad_perm:[2,3,0,1] row_mask:0xf bank_mask:0xf bound_ctrl:1
	s_nop 1
	v_add_f32_dpp v35, v35, v35 row_half_mirror row_mask:0xf bank_mask:0xf bound_ctrl:1
	s_nop 1
	v_add_f32_dpp v35, v35, v35 row_mirror row_mask:0xf bank_mask:0xf bound_ctrl:1
	ds_swizzle_b32 v36, v35 offset:swizzle(SWAP,16)
	s_waitcnt lgkmcnt(0)
	v_add_f32_e32 v35, v35, v36
	v_mov_b32_e32 v36, v35
	s_nop 1
	v_permlane32_swap_b32_e32 v35, v36
	v_add_f32_e32 v35, v35, v36
	v_fmamk_f32 v35, v35, 0x3c000000, v206
	v_cmp_gt_f32_e32 vcc, s21, v35
	v_mul_f32_e32 v36, 0x4f800000, v35
	s_nop 0
	v_cndmask_b32_e32 v35, v35, v36, vcc
	v_sqrt_f32_e32 v36, v35
	s_nop 0
	v_add_u32_e32 v37, -1, v36
	v_fma_f32 v44, -v37, v36, v35
	v_cmp_ge_f32_e64 s[0:1], 0, v44
	v_add_u32_e32 v44, 1, v36
	s_nop 0
	v_cndmask_b32_e64 v37, v36, v37, s[0:1]
	v_fma_f32 v36, -v44, v36, v35
	v_cmp_lt_f32_e64 s[0:1], 0, v36
	s_nop 1
	v_cndmask_b32_e64 v36, v37, v44, s[0:1]
	v_mul_f32_e32 v37, 0x37800000, v36
	v_cndmask_b32_e32 v36, v36, v37, vcc
	v_cmp_class_f32_e32 vcc, v35, v207
	s_nop 1
	v_cndmask_b32_e32 v35, v36, v35, vcc
	v_div_scale_f32 v36, s[0:1], v35, v35, 1.0
	v_rcp_f32_e32 v37, v36
	s_nop 0
	v_fma_f32 v44, -v36, v37, 1.0
	v_fmac_f32_e32 v37, v44, v37
	v_div_scale_f32 v44, vcc, 1.0, v35, 1.0
	v_mul_f32_e32 v45, v44, v37
	v_fma_f32 v46, -v36, v45, v44
	v_fmac_f32_e32 v45, v46, v37
	v_fma_f32 v36, -v36, v45, v44
	v_div_fmas_f32 v36, v36, v37, v45
	v_div_fixup_f32 v35, v36, v35, 1.0
	s_waitcnt vmcnt(27)
	v_lshlrev_b32_e32 v36, 16, v38
	v_mul_f32_e32 v37, 0xbfb8aa3b, v36
	v_exp_f32_e32 v37, v37
	v_mul_f32_e32 v31, v35, v31
	v_mul_f32_e32 v31, v6, v31
	v_mul_f32_e32 v34, v35, v34
	v_add_f32_e32 v37, 1.0, v37
	v_rcp_f32_e32 v37, v37
	v_and_b32_e32 v35, 0xffff0000, v38
	v_mul_f32_e32 v34, v7, v34
	v_mul_f32_e32 v36, v37, v36
	v_mul_f32_e32 v31, v36, v31
	v_mul_f32_e32 v36, 0xbfb8aa3b, v35
	v_exp_f32_e32 v36, v36
	s_nop 0
	v_add_f32_e32 v36, 1.0, v36
	v_rcp_f32_e32 v36, v36
	s_nop 0
	v_mul_f32_e32 v35, v36, v35
	v_mul_f32_e32 v34, v35, v34
	v_bfe_u32 v35, v31, 16, 1
	v_add3_u32 v31, v31, v35, s18
	v_bfe_u32 v35, v34, 16, 1
	v_lshrrev_b32_e32 v31, 16, v31
	v_add3_u32 v34, v34, v35, s18
	v_and_or_b32 v31, v34, s19, v31
	global_store_dword v[32:33], v31, off
	v_and_b32_e32 v32, 0xffff0000, v39
	v_lshlrev_b32_e32 v31, 16, v39
	v_mul_f32_e32 v33, v32, v32
	v_fmac_f32_e32 v33, v31, v31
	s_nop 1
	v_add_f32_dpp v33, v33, v33 quad_perm:[1,0,3,2] row_mask:0xf bank_mask:0xf bound_ctrl:1
	s_nop 1
	v_add_f32_dpp v33, v33, v33 quad_perm:[2,3,0,1] row_mask:0xf bank_mask:0xf bound_ctrl:1
	s_nop 1
	v_add_f32_dpp v33, v33, v33 row_half_mirror row_mask:0xf bank_mask:0xf bound_ctrl:1
	s_nop 1
	v_add_f32_dpp v33, v33, v33 row_mirror row_mask:0xf bank_mask:0xf bound_ctrl:1
	ds_swizzle_b32 v34, v33 offset:swizzle(SWAP,16)
	s_waitcnt lgkmcnt(0)
	v_add_f32_e32 v33, v33, v34
	v_mov_b32_e32 v34, v33
	s_nop 1
	v_permlane32_swap_b32_e32 v33, v34
	v_add_f32_e32 v33, v33, v34
	v_fmamk_f32 v33, v33, 0x3c000000, v206
	v_cmp_gt_f32_e32 vcc, s21, v33
	v_mul_f32_e32 v34, 0x4f800000, v33
	s_nop 0
	v_cndmask_b32_e32 v33, v33, v34, vcc
	v_sqrt_f32_e32 v34, v33
	s_nop 0
	v_add_u32_e32 v35, -1, v34
	v_fma_f32 v36, -v35, v34, v33
	v_cmp_ge_f32_e64 s[0:1], 0, v36
	v_add_u32_e32 v36, 1, v34
	s_nop 0
	v_cndmask_b32_e64 v35, v34, v35, s[0:1]
	v_fma_f32 v34, -v36, v34, v33
	v_cmp_lt_f32_e64 s[0:1], 0, v34
	s_nop 1
	v_cndmask_b32_e64 v34, v35, v36, s[0:1]
	v_mul_f32_e32 v35, 0x37800000, v34
	v_cndmask_b32_e32 v34, v34, v35, vcc
	v_cmp_class_f32_e32 vcc, v33, v207
	s_nop 1
	v_cndmask_b32_e32 v33, v34, v33, vcc
	v_div_scale_f32 v34, s[0:1], v33, v33, 1.0
	v_rcp_f32_e32 v35, v34
	s_nop 0
	v_fma_f32 v36, -v34, v35, 1.0
	v_fmac_f32_e32 v35, v36, v35
	v_div_scale_f32 v36, vcc, 1.0, v33, 1.0
	v_mul_f32_e32 v37, v36, v35
	v_fma_f32 v38, -v34, v37, v36
	v_fmac_f32_e32 v37, v38, v35
	v_fma_f32 v34, -v34, v37, v36
	v_div_fmas_f32 v34, v34, v35, v37
	v_div_fixup_f32 v33, v34, v33, 1.0
	s_waitcnt vmcnt(27)
	v_lshlrev_b32_e32 v34, 16, v40
	v_mul_f32_e32 v35, 0xbfb8aa3b, v34
	v_exp_f32_e32 v35, v35
	v_mul_f32_e32 v31, v33, v31
	v_mul_f32_e32 v31, v6, v31
	v_mul_f32_e32 v32, v33, v32
	v_add_f32_e32 v35, 1.0, v35
	v_rcp_f32_e32 v35, v35
	v_and_b32_e32 v33, 0xffff0000, v40
	v_mul_f32_e32 v32, v7, v32
	v_mul_f32_e32 v34, v35, v34
	v_mul_f32_e32 v31, v34, v31
	v_mul_f32_e32 v34, 0xbfb8aa3b, v33
	v_exp_f32_e32 v34, v34
	s_nop 0
	v_add_f32_e32 v34, 1.0, v34
	v_rcp_f32_e32 v34, v34
	s_nop 0
	v_mul_f32_e32 v33, v34, v33
	v_mul_f32_e32 v32, v33, v32
	v_bfe_u32 v33, v31, 16, 1
	v_add3_u32 v31, v31, v33, s18
	v_bfe_u32 v33, v32, 16, 1
	v_lshrrev_b32_e32 v31, 16, v31
	v_add3_u32 v32, v32, v33, s18
	v_and_or_b32 v31, v32, s19, v31
	v_add_co_u32_e32 v32, vcc, s16, v8
	s_waitcnt vmcnt(26)
	v_and_b32_e32 v34, 0xffff0000, v41
	v_addc_co_u32_e32 v33, vcc, 0, v9, vcc
	global_store_dword v[32:33], v31, off offset:-4096
	v_lshlrev_b32_e32 v31, 16, v41
	v_mul_f32_e32 v35, v34, v34
	v_fmac_f32_e32 v35, v31, v31
	s_nop 1
	v_add_f32_dpp v35, v35, v35 quad_perm:[1,0,3,2] row_mask:0xf bank_mask:0xf bound_ctrl:1
	s_nop 1
	v_add_f32_dpp v35, v35, v35 quad_perm:[2,3,0,1] row_mask:0xf bank_mask:0xf bound_ctrl:1
	s_nop 1
	v_add_f32_dpp v35, v35, v35 row_half_mirror row_mask:0xf bank_mask:0xf bound_ctrl:1
	s_nop 1
	v_add_f32_dpp v35, v35, v35 row_mirror row_mask:0xf bank_mask:0xf bound_ctrl:1
	ds_swizzle_b32 v36, v35 offset:swizzle(SWAP,16)
	s_waitcnt lgkmcnt(0)
	v_add_f32_e32 v35, v35, v36
	v_mov_b32_e32 v36, v35
	s_nop 1
	v_permlane32_swap_b32_e32 v35, v36
	v_add_f32_e32 v35, v35, v36
	v_fmamk_f32 v35, v35, 0x3c000000, v206
	v_cmp_gt_f32_e32 vcc, s21, v35
	v_mul_f32_e32 v36, 0x4f800000, v35
	s_nop 0
	v_cndmask_b32_e32 v35, v35, v36, vcc
	v_sqrt_f32_e32 v36, v35
	s_nop 0
	v_add_u32_e32 v37, -1, v36
	v_fma_f32 v38, -v37, v36, v35
	v_cmp_ge_f32_e64 s[0:1], 0, v38
	v_add_u32_e32 v38, 1, v36
	s_nop 0
	v_cndmask_b32_e64 v37, v36, v37, s[0:1]
	v_fma_f32 v36, -v38, v36, v35
	v_cmp_lt_f32_e64 s[0:1], 0, v36
	s_nop 1
	v_cndmask_b32_e64 v36, v37, v38, s[0:1]
	v_mul_f32_e32 v37, 0x37800000, v36
	v_cndmask_b32_e32 v36, v36, v37, vcc
	v_cmp_class_f32_e32 vcc, v35, v207
	s_nop 1
	v_cndmask_b32_e32 v35, v36, v35, vcc
	v_div_scale_f32 v36, s[0:1], v35, v35, 1.0
	v_rcp_f32_e32 v37, v36
	s_nop 0
	v_fma_f32 v38, -v36, v37, 1.0
	v_fmac_f32_e32 v37, v38, v37
	v_div_scale_f32 v38, vcc, 1.0, v35, 1.0
	v_mul_f32_e32 v39, v38, v37
	v_fma_f32 v40, -v36, v39, v38
	v_fmac_f32_e32 v39, v40, v37
	v_fma_f32 v36, -v36, v39, v38
	v_div_fmas_f32 v36, v36, v37, v39
	v_div_fixup_f32 v35, v36, v35, 1.0
	s_waitcnt vmcnt(25)
	v_lshlrev_b32_e32 v36, 16, v42
	v_mul_f32_e32 v37, 0xbfb8aa3b, v36
	v_exp_f32_e32 v37, v37
	v_mul_f32_e32 v31, v35, v31
	v_mul_f32_e32 v31, v6, v31
	v_mul_f32_e32 v34, v35, v34
	v_add_f32_e32 v37, 1.0, v37
	v_rcp_f32_e32 v37, v37
	v_and_b32_e32 v35, 0xffff0000, v42
	v_mul_f32_e32 v34, v7, v34
	v_mul_f32_e32 v36, v37, v36
	v_mul_f32_e32 v31, v36, v31
	v_mul_f32_e32 v36, 0xbfb8aa3b, v35
	v_exp_f32_e32 v36, v36
	s_nop 0
	v_add_f32_e32 v36, 1.0, v36
	v_rcp_f32_e32 v36, v36
	s_nop 0
	v_mul_f32_e32 v35, v36, v35
	v_mul_f32_e32 v34, v35, v34
	v_bfe_u32 v35, v31, 16, 1
	v_add3_u32 v31, v31, v35, s18
	v_bfe_u32 v35, v34, 16, 1
	v_lshrrev_b32_e32 v31, 16, v31
	v_add3_u32 v34, v34, v35, s18
	v_and_or_b32 v31, v34, s19, v31
	global_store_dword v[32:33], v31, off
	v_and_b32_e32 v32, 0xffff0000, v43
	v_lshlrev_b32_e32 v31, 16, v43
	v_mul_f32_e32 v33, v32, v32
	v_fmac_f32_e32 v33, v31, v31
	s_nop 1
	v_add_f32_dpp v33, v33, v33 quad_perm:[1,0,3,2] row_mask:0xf bank_mask:0xf bound_ctrl:1
	s_nop 1
	v_add_f32_dpp v33, v33, v33 quad_perm:[2,3,0,1] row_mask:0xf bank_mask:0xf bound_ctrl:1
	s_nop 1
	v_add_f32_dpp v33, v33, v33 row_half_mirror row_mask:0xf bank_mask:0xf bound_ctrl:1
	s_nop 1
	v_add_f32_dpp v33, v33, v33 row_mirror row_mask:0xf bank_mask:0xf bound_ctrl:1
	ds_swizzle_b32 v34, v33 offset:swizzle(SWAP,16)
	s_waitcnt lgkmcnt(0)
	v_add_f32_e32 v33, v33, v34
	v_mov_b32_e32 v34, v33
	s_nop 1
	v_permlane32_swap_b32_e32 v33, v34
	v_add_f32_e32 v33, v33, v34
	v_fmamk_f32 v33, v33, 0x3c000000, v206
	v_cmp_gt_f32_e32 vcc, s21, v33
	v_mul_f32_e32 v34, 0x4f800000, v33
	s_nop 0
	v_cndmask_b32_e32 v33, v33, v34, vcc
	v_sqrt_f32_e32 v34, v33
	s_nop 0
	v_add_u32_e32 v35, -1, v34
	v_fma_f32 v36, -v35, v34, v33
	v_cmp_ge_f32_e64 s[0:1], 0, v36
	v_add_u32_e32 v36, 1, v34
	s_nop 0
	v_cndmask_b32_e64 v35, v34, v35, s[0:1]
	v_fma_f32 v34, -v36, v34, v33
	v_cmp_lt_f32_e64 s[0:1], 0, v34
	s_nop 1
	v_cndmask_b32_e64 v34, v35, v36, s[0:1]
	v_mul_f32_e32 v35, 0x37800000, v34
	v_cndmask_b32_e32 v34, v34, v35, vcc
	v_cmp_class_f32_e32 vcc, v33, v207
	s_nop 1
	v_cndmask_b32_e32 v33, v34, v33, vcc
	v_div_scale_f32 v34, s[0:1], v33, v33, 1.0
	v_rcp_f32_e32 v35, v34
	s_nop 0
	v_fma_f32 v36, -v34, v35, 1.0
	v_fmac_f32_e32 v35, v36, v35
	v_div_scale_f32 v36, vcc, 1.0, v33, 1.0
	v_mul_f32_e32 v37, v36, v35
	v_fma_f32 v38, -v34, v37, v36
	v_fmac_f32_e32 v37, v38, v35
	v_fma_f32 v34, -v34, v37, v36
	v_div_fmas_f32 v34, v34, v35, v37
	v_div_fixup_f32 v33, v34, v33, 1.0
	s_waitcnt vmcnt(25)
	v_lshlrev_b32_e32 v34, 16, v30
	v_mul_f32_e32 v35, 0xbfb8aa3b, v34
	v_and_b32_e32 v30, 0xffff0000, v30
	v_mul_f32_e32 v31, v33, v31
	v_exp_f32_e32 v35, v35
	v_mul_f32_e32 v32, v33, v32
	v_mul_f32_e32 v33, 0xbfb8aa3b, v30
	v_exp_f32_e32 v33, v33
	v_add_f32_e32 v35, 1.0, v35
	v_rcp_f32_e32 v35, v35
	v_mul_f32_e32 v31, v6, v31
	v_add_f32_e32 v33, 1.0, v33
	v_rcp_f32_e32 v33, v33
	v_mul_f32_e32 v34, v35, v34
	v_mul_f32_e32 v31, v34, v31
	v_mul_f32_e32 v32, v7, v32
	v_mul_f32_e32 v30, v33, v30
	v_mul_f32_e32 v30, v30, v32
	v_bfe_u32 v32, v31, 16, 1
	v_add3_u32 v31, v31, v32, s18
	v_bfe_u32 v32, v30, 16, 1
	v_lshrrev_b32_e32 v31, 16, v31
	v_add3_u32 v30, v30, v32, s18
	v_and_or_b32 v32, v30, s19, v31
	v_add_co_u32_e32 v30, vcc, s15, v8
	s_nop 1
	v_addc_co_u32_e32 v31, vcc, 0, v9, vcc
	global_store_dword v[30:31], v32, off offset:-4096
	s_waitcnt vmcnt(25)
	v_lshlrev_b32_e32 v32, 16, v29
	v_and_b32_e32 v29, 0xffff0000, v29
	v_mul_f32_e32 v33, v29, v29
	v_fmac_f32_e32 v33, v32, v32
	s_nop 1
	v_add_f32_dpp v33, v33, v33 quad_perm:[1,0,3,2] row_mask:0xf bank_mask:0xf bound_ctrl:1
	s_nop 1
	v_add_f32_dpp v33, v33, v33 quad_perm:[2,3,0,1] row_mask:0xf bank_mask:0xf bound_ctrl:1
	s_nop 1
	v_add_f32_dpp v33, v33, v33 row_half_mirror row_mask:0xf bank_mask:0xf bound_ctrl:1
	s_nop 1
	v_add_f32_dpp v33, v33, v33 row_mirror row_mask:0xf bank_mask:0xf bound_ctrl:1
	ds_swizzle_b32 v34, v33 offset:swizzle(SWAP,16)
	s_waitcnt lgkmcnt(0)
	v_add_f32_e32 v33, v33, v34
	v_mov_b32_e32 v34, v33
	s_nop 1
	v_permlane32_swap_b32_e32 v33, v34
	v_add_f32_e32 v33, v33, v34
	v_fmamk_f32 v33, v33, 0x3c000000, v206
	v_cmp_gt_f32_e32 vcc, s21, v33
	v_mul_f32_e32 v34, 0x4f800000, v33
	s_nop 0
	v_cndmask_b32_e32 v33, v33, v34, vcc
	v_sqrt_f32_e32 v34, v33
	s_nop 0
	v_add_u32_e32 v35, -1, v34
	v_fma_f32 v36, -v35, v34, v33
	v_cmp_ge_f32_e64 s[0:1], 0, v36
	v_add_u32_e32 v36, 1, v34
	s_nop 0
	v_cndmask_b32_e64 v35, v34, v35, s[0:1]
	v_fma_f32 v34, -v36, v34, v33
	v_cmp_lt_f32_e64 s[0:1], 0, v34
	s_nop 1
	v_cndmask_b32_e64 v34, v35, v36, s[0:1]
	v_mul_f32_e32 v35, 0x37800000, v34
	v_cndmask_b32_e32 v34, v34, v35, vcc
	v_cmp_class_f32_e32 vcc, v33, v207
	s_nop 1
	v_cndmask_b32_e32 v33, v34, v33, vcc
	v_div_scale_f32 v34, s[0:1], v33, v33, 1.0
	v_rcp_f32_e32 v35, v34
	s_nop 0
	v_fma_f32 v36, -v34, v35, 1.0
	v_fmac_f32_e32 v35, v36, v35
	v_div_scale_f32 v36, vcc, 1.0, v33, 1.0
	v_mul_f32_e32 v37, v36, v35
	v_fma_f32 v38, -v34, v37, v36
	v_fmac_f32_e32 v37, v38, v35
	v_fma_f32 v34, -v34, v37, v36
	v_div_fmas_f32 v34, v34, v35, v37
	v_div_fixup_f32 v33, v34, v33, 1.0
	s_waitcnt vmcnt(24)
	v_lshlrev_b32_e32 v34, 16, v28
	v_mul_f32_e32 v35, 0xbfb8aa3b, v34
	v_and_b32_e32 v28, 0xffff0000, v28
	v_mul_f32_e32 v32, v33, v32
	v_exp_f32_e32 v35, v35
	v_mul_f32_e32 v29, v33, v29
	v_mul_f32_e32 v33, 0xbfb8aa3b, v28
	v_exp_f32_e32 v33, v33
	v_add_f32_e32 v35, 1.0, v35
	v_rcp_f32_e32 v35, v35
	v_mul_f32_e32 v32, v6, v32
	v_add_f32_e32 v33, 1.0, v33
	v_rcp_f32_e32 v33, v33
	v_mul_f32_e32 v34, v35, v34
	v_mul_f32_e32 v32, v34, v32
	v_mul_f32_e32 v29, v7, v29
	v_mul_f32_e32 v28, v33, v28
	v_mul_f32_e32 v28, v28, v29
	v_bfe_u32 v29, v32, 16, 1
	v_add3_u32 v29, v32, v29, s18
	v_bfe_u32 v32, v28, 16, 1
	v_lshrrev_b32_e32 v29, 16, v29
	v_add3_u32 v28, v28, v32, s18
	v_and_or_b32 v28, v28, s19, v29
	global_store_dword v[30:31], v28, off
	s_waitcnt vmcnt(24)
	v_lshlrev_b32_e32 v28, 16, v27
	v_and_b32_e32 v27, 0xffff0000, v27
	v_mul_f32_e32 v29, v27, v27
	v_fmac_f32_e32 v29, v28, v28
	s_nop 1
	v_add_f32_dpp v29, v29, v29 quad_perm:[1,0,3,2] row_mask:0xf bank_mask:0xf bound_ctrl:1
	s_nop 1
	v_add_f32_dpp v29, v29, v29 quad_perm:[2,3,0,1] row_mask:0xf bank_mask:0xf bound_ctrl:1
	s_nop 1
	v_add_f32_dpp v29, v29, v29 row_half_mirror row_mask:0xf bank_mask:0xf bound_ctrl:1
	s_nop 1
	v_add_f32_dpp v29, v29, v29 row_mirror row_mask:0xf bank_mask:0xf bound_ctrl:1
	ds_swizzle_b32 v30, v29 offset:swizzle(SWAP,16)
	s_waitcnt lgkmcnt(0)
	v_add_f32_e32 v29, v29, v30
	v_mov_b32_e32 v30, v29
	s_nop 1
	v_permlane32_swap_b32_e32 v29, v30
	v_add_f32_e32 v29, v29, v30
	v_fmamk_f32 v29, v29, 0x3c000000, v206
	v_cmp_gt_f32_e32 vcc, s21, v29
	v_mul_f32_e32 v30, 0x4f800000, v29
	s_nop 0
	v_cndmask_b32_e32 v29, v29, v30, vcc
	v_sqrt_f32_e32 v30, v29
	s_nop 0
	v_add_u32_e32 v31, -1, v30
	v_fma_f32 v32, -v31, v30, v29
	v_cmp_ge_f32_e64 s[0:1], 0, v32
	v_add_u32_e32 v32, 1, v30
	s_nop 0
	v_cndmask_b32_e64 v31, v30, v31, s[0:1]
	v_fma_f32 v30, -v32, v30, v29
	v_cmp_lt_f32_e64 s[0:1], 0, v30
	s_nop 1
	v_cndmask_b32_e64 v30, v31, v32, s[0:1]
	v_mul_f32_e32 v31, 0x37800000, v30
	v_cndmask_b32_e32 v30, v30, v31, vcc
	v_cmp_class_f32_e32 vcc, v29, v207
	s_nop 1
	v_cndmask_b32_e32 v29, v30, v29, vcc
	v_div_scale_f32 v30, s[0:1], v29, v29, 1.0
	v_rcp_f32_e32 v31, v30
	s_nop 0
	v_fma_f32 v32, -v30, v31, 1.0
	v_fmac_f32_e32 v31, v32, v31
	v_div_scale_f32 v32, vcc, 1.0, v29, 1.0
	v_mul_f32_e32 v33, v32, v31
	v_fma_f32 v34, -v30, v33, v32
	v_fmac_f32_e32 v33, v34, v31
	v_fma_f32 v30, -v30, v33, v32
	v_div_fmas_f32 v30, v30, v31, v33
	v_div_fixup_f32 v29, v30, v29, 1.0
	s_waitcnt vmcnt(23)
	v_lshlrev_b32_e32 v30, 16, v26
	v_mul_f32_e32 v31, 0xbfb8aa3b, v30
	v_and_b32_e32 v26, 0xffff0000, v26
	v_mul_f32_e32 v28, v29, v28
	v_exp_f32_e32 v31, v31
	v_mul_f32_e32 v27, v29, v27
	v_mul_f32_e32 v29, 0xbfb8aa3b, v26
	v_exp_f32_e32 v29, v29
	v_add_f32_e32 v31, 1.0, v31
	v_rcp_f32_e32 v31, v31
	v_mul_f32_e32 v28, v6, v28
	v_add_f32_e32 v29, 1.0, v29
	v_rcp_f32_e32 v29, v29
	v_mul_f32_e32 v30, v31, v30
	v_mul_f32_e32 v28, v30, v28
	v_mul_f32_e32 v27, v7, v27
	v_mul_f32_e32 v26, v29, v26
	v_mul_f32_e32 v26, v26, v27
	v_bfe_u32 v27, v28, 16, 1
	v_add3_u32 v27, v28, v27, s18
	v_bfe_u32 v28, v26, 16, 1
	v_lshrrev_b32_e32 v27, 16, v27
	v_add3_u32 v26, v26, v28, s18
	v_and_or_b32 v28, v26, s19, v27
	v_add_co_u32_e32 v26, vcc, s14, v8
	s_nop 1
	v_addc_co_u32_e32 v27, vcc, 0, v9, vcc
	global_store_dword v[26:27], v28, off offset:-4096
	s_waitcnt vmcnt(23)
	v_lshlrev_b32_e32 v28, 16, v25
	v_and_b32_e32 v25, 0xffff0000, v25
	v_mul_f32_e32 v29, v25, v25
	v_fmac_f32_e32 v29, v28, v28
	s_nop 1
	v_add_f32_dpp v29, v29, v29 quad_perm:[1,0,3,2] row_mask:0xf bank_mask:0xf bound_ctrl:1
	s_nop 1
	v_add_f32_dpp v29, v29, v29 quad_perm:[2,3,0,1] row_mask:0xf bank_mask:0xf bound_ctrl:1
	s_nop 1
	v_add_f32_dpp v29, v29, v29 row_half_mirror row_mask:0xf bank_mask:0xf bound_ctrl:1
	s_nop 1
	v_add_f32_dpp v29, v29, v29 row_mirror row_mask:0xf bank_mask:0xf bound_ctrl:1
	ds_swizzle_b32 v30, v29 offset:swizzle(SWAP,16)
	s_waitcnt lgkmcnt(0)
	v_add_f32_e32 v29, v29, v30
	v_mov_b32_e32 v30, v29
	s_nop 1
	v_permlane32_swap_b32_e32 v29, v30
	v_add_f32_e32 v29, v29, v30
	v_fmamk_f32 v29, v29, 0x3c000000, v206
	v_cmp_gt_f32_e32 vcc, s21, v29
	v_mul_f32_e32 v30, 0x4f800000, v29
	s_nop 0
	v_cndmask_b32_e32 v29, v29, v30, vcc
	v_sqrt_f32_e32 v30, v29
	s_nop 0
	v_add_u32_e32 v31, -1, v30
	v_fma_f32 v32, -v31, v30, v29
	v_cmp_ge_f32_e64 s[0:1], 0, v32
	v_add_u32_e32 v32, 1, v30
	s_nop 0
	v_cndmask_b32_e64 v31, v30, v31, s[0:1]
	v_fma_f32 v30, -v32, v30, v29
	v_cmp_lt_f32_e64 s[0:1], 0, v30
	s_nop 1
	v_cndmask_b32_e64 v30, v31, v32, s[0:1]
	v_mul_f32_e32 v31, 0x37800000, v30
	v_cndmask_b32_e32 v30, v30, v31, vcc
	v_cmp_class_f32_e32 vcc, v29, v207
	s_nop 1
	v_cndmask_b32_e32 v29, v30, v29, vcc
	v_div_scale_f32 v30, s[0:1], v29, v29, 1.0
	v_rcp_f32_e32 v31, v30
	s_nop 0
	v_fma_f32 v32, -v30, v31, 1.0
	v_fmac_f32_e32 v31, v32, v31
	v_div_scale_f32 v32, vcc, 1.0, v29, 1.0
	v_mul_f32_e32 v33, v32, v31
	v_fma_f32 v34, -v30, v33, v32
	v_fmac_f32_e32 v33, v34, v31
	v_fma_f32 v30, -v30, v33, v32
	v_div_fmas_f32 v30, v30, v31, v33
	v_div_fixup_f32 v29, v30, v29, 1.0
	s_waitcnt vmcnt(22)
	v_lshlrev_b32_e32 v30, 16, v24
	v_mul_f32_e32 v31, 0xbfb8aa3b, v30
	v_and_b32_e32 v24, 0xffff0000, v24
	v_mul_f32_e32 v28, v29, v28
	v_exp_f32_e32 v31, v31
	v_mul_f32_e32 v25, v29, v25
	v_mul_f32_e32 v29, 0xbfb8aa3b, v24
	v_exp_f32_e32 v29, v29
	v_add_f32_e32 v31, 1.0, v31
	v_rcp_f32_e32 v31, v31
	v_mul_f32_e32 v28, v6, v28
	v_add_f32_e32 v29, 1.0, v29
	v_rcp_f32_e32 v29, v29
	v_mul_f32_e32 v30, v31, v30
	v_mul_f32_e32 v28, v30, v28
	v_mul_f32_e32 v25, v7, v25
	v_mul_f32_e32 v24, v29, v24
	v_mul_f32_e32 v24, v24, v25
	v_bfe_u32 v25, v28, 16, 1
	v_add3_u32 v25, v28, v25, s18
	v_bfe_u32 v28, v24, 16, 1
	v_lshrrev_b32_e32 v25, 16, v25
	v_add3_u32 v24, v24, v28, s18
	v_and_or_b32 v24, v24, s19, v25
	global_store_dword v[26:27], v24, off
	s_waitcnt vmcnt(22)
	v_lshlrev_b32_e32 v24, 16, v23
	v_and_b32_e32 v23, 0xffff0000, v23
	v_mul_f32_e32 v25, v23, v23
	v_fmac_f32_e32 v25, v24, v24
	s_nop 1
	v_add_f32_dpp v25, v25, v25 quad_perm:[1,0,3,2] row_mask:0xf bank_mask:0xf bound_ctrl:1
	s_nop 1
	v_add_f32_dpp v25, v25, v25 quad_perm:[2,3,0,1] row_mask:0xf bank_mask:0xf bound_ctrl:1
	s_nop 1
	v_add_f32_dpp v25, v25, v25 row_half_mirror row_mask:0xf bank_mask:0xf bound_ctrl:1
	s_nop 1
	v_add_f32_dpp v25, v25, v25 row_mirror row_mask:0xf bank_mask:0xf bound_ctrl:1
	ds_swizzle_b32 v26, v25 offset:swizzle(SWAP,16)
	s_waitcnt lgkmcnt(0)
	v_add_f32_e32 v25, v25, v26
	v_mov_b32_e32 v26, v25
	s_nop 1
	v_permlane32_swap_b32_e32 v25, v26
	v_add_f32_e32 v25, v25, v26
	v_fmamk_f32 v25, v25, 0x3c000000, v206
	v_cmp_gt_f32_e32 vcc, s21, v25
	v_mul_f32_e32 v26, 0x4f800000, v25
	s_nop 0
	v_cndmask_b32_e32 v25, v25, v26, vcc
	v_sqrt_f32_e32 v26, v25
	s_nop 0
	v_add_u32_e32 v27, -1, v26
	v_fma_f32 v28, -v27, v26, v25
	v_cmp_ge_f32_e64 s[0:1], 0, v28
	v_add_u32_e32 v28, 1, v26
	s_nop 0
	v_cndmask_b32_e64 v27, v26, v27, s[0:1]
	v_fma_f32 v26, -v28, v26, v25
	v_cmp_lt_f32_e64 s[0:1], 0, v26
	s_nop 1
	v_cndmask_b32_e64 v26, v27, v28, s[0:1]
	v_mul_f32_e32 v27, 0x37800000, v26
	v_cndmask_b32_e32 v26, v26, v27, vcc
	v_cmp_class_f32_e32 vcc, v25, v207
	s_nop 1
	v_cndmask_b32_e32 v25, v26, v25, vcc
	v_div_scale_f32 v26, s[0:1], v25, v25, 1.0
	v_rcp_f32_e32 v27, v26
	s_mov_b32 s0, 0xa000
	v_fma_f32 v28, -v26, v27, 1.0
	v_fmac_f32_e32 v27, v28, v27
	v_div_scale_f32 v28, vcc, 1.0, v25, 1.0
	v_mul_f32_e32 v29, v28, v27
	v_fma_f32 v30, -v26, v29, v28
	v_fmac_f32_e32 v29, v30, v27
	v_fma_f32 v26, -v26, v29, v28
	v_div_fmas_f32 v26, v26, v27, v29
	v_div_fixup_f32 v25, v26, v25, 1.0
	s_waitcnt vmcnt(21)
	v_lshlrev_b32_e32 v26, 16, v22
	v_mul_f32_e32 v27, 0xbfb8aa3b, v26
	v_and_b32_e32 v22, 0xffff0000, v22
	v_mul_f32_e32 v24, v25, v24
	v_exp_f32_e32 v27, v27
	v_mul_f32_e32 v23, v25, v23
	v_mul_f32_e32 v25, 0xbfb8aa3b, v22
	v_exp_f32_e32 v25, v25
	v_add_f32_e32 v27, 1.0, v27
	v_rcp_f32_e32 v27, v27
	v_mul_f32_e32 v24, v6, v24
	v_add_f32_e32 v25, 1.0, v25
	v_rcp_f32_e32 v25, v25
	v_mul_f32_e32 v26, v27, v26
	v_mul_f32_e32 v24, v26, v24
	v_mul_f32_e32 v23, v7, v23
	v_mul_f32_e32 v22, v25, v22
	v_mul_f32_e32 v22, v22, v23
	v_bfe_u32 v23, v24, 16, 1
	v_add3_u32 v23, v24, v23, s18
	v_bfe_u32 v24, v22, 16, 1
	v_lshrrev_b32_e32 v23, 16, v23
	v_add3_u32 v22, v22, v24, s18
	v_add_co_u32_e32 v24, vcc, s0, v8
	v_and_or_b32 v22, v22, s19, v23
	s_nop 0
	v_addc_co_u32_e32 v25, vcc, 0, v9, vcc
	global_store_dword v[24:25], v22, off offset:-4096
	s_waitcnt vmcnt(21)
	v_lshlrev_b32_e32 v22, 16, v21
	v_and_b32_e32 v21, 0xffff0000, v21
	v_mul_f32_e32 v23, v21, v21
	v_fmac_f32_e32 v23, v22, v22
	s_nop 1
	v_add_f32_dpp v23, v23, v23 quad_perm:[1,0,3,2] row_mask:0xf bank_mask:0xf bound_ctrl:1
	s_nop 1
	v_add_f32_dpp v23, v23, v23 quad_perm:[2,3,0,1] row_mask:0xf bank_mask:0xf bound_ctrl:1
	s_nop 1
	v_add_f32_dpp v23, v23, v23 row_half_mirror row_mask:0xf bank_mask:0xf bound_ctrl:1
	s_nop 1
	v_add_f32_dpp v23, v23, v23 row_mirror row_mask:0xf bank_mask:0xf bound_ctrl:1
	ds_swizzle_b32 v26, v23 offset:swizzle(SWAP,16)
	s_waitcnt lgkmcnt(0)
	v_add_f32_e32 v23, v23, v26
	v_mov_b32_e32 v26, v23
	s_nop 1
	v_permlane32_swap_b32_e32 v23, v26
	v_add_f32_e32 v23, v23, v26
	v_fmamk_f32 v23, v23, 0x3c000000, v206
	v_cmp_gt_f32_e32 vcc, s21, v23
	v_mul_f32_e32 v26, 0x4f800000, v23
	s_nop 0
	v_cndmask_b32_e32 v23, v23, v26, vcc
	v_sqrt_f32_e32 v26, v23
	s_nop 0
	v_add_u32_e32 v27, -1, v26
	v_fma_f32 v28, -v27, v26, v23
	v_cmp_ge_f32_e64 s[0:1], 0, v28
	v_add_u32_e32 v28, 1, v26
	s_nop 0
	v_cndmask_b32_e64 v27, v26, v27, s[0:1]
	v_fma_f32 v26, -v28, v26, v23
	v_cmp_lt_f32_e64 s[0:1], 0, v26
	s_nop 1
	v_cndmask_b32_e64 v26, v27, v28, s[0:1]
	v_mul_f32_e32 v27, 0x37800000, v26
	v_cndmask_b32_e32 v26, v26, v27, vcc
	v_cmp_class_f32_e32 vcc, v23, v207
	s_nop 1
	v_cndmask_b32_e32 v23, v26, v23, vcc
	v_div_scale_f32 v26, s[0:1], v23, v23, 1.0
	v_rcp_f32_e32 v27, v26
	s_nop 0
	v_fma_f32 v28, -v26, v27, 1.0
	v_fmac_f32_e32 v27, v28, v27
	v_div_scale_f32 v28, vcc, 1.0, v23, 1.0
	v_mul_f32_e32 v29, v28, v27
	v_fma_f32 v30, -v26, v29, v28
	v_fmac_f32_e32 v29, v30, v27
	v_fma_f32 v26, -v26, v29, v28
	v_div_fmas_f32 v26, v26, v27, v29
	v_div_fixup_f32 v23, v26, v23, 1.0
	s_waitcnt vmcnt(20)
	v_lshlrev_b32_e32 v26, 16, v20
	v_mul_f32_e32 v27, 0xbfb8aa3b, v26
	v_and_b32_e32 v20, 0xffff0000, v20
	v_mul_f32_e32 v22, v23, v22
	v_exp_f32_e32 v27, v27
	v_mul_f32_e32 v21, v23, v21
	v_mul_f32_e32 v23, 0xbfb8aa3b, v20
	v_exp_f32_e32 v23, v23
	v_add_f32_e32 v27, 1.0, v27
	v_rcp_f32_e32 v27, v27
	v_mul_f32_e32 v22, v6, v22
	v_add_f32_e32 v23, 1.0, v23
	v_rcp_f32_e32 v23, v23
	v_mul_f32_e32 v26, v27, v26
	v_mul_f32_e32 v22, v26, v22
	v_mul_f32_e32 v21, v7, v21
	v_mul_f32_e32 v20, v23, v20
	v_mul_f32_e32 v20, v20, v21
	v_bfe_u32 v21, v22, 16, 1
	v_add3_u32 v21, v22, v21, s18
	v_bfe_u32 v22, v20, 16, 1
	v_lshrrev_b32_e32 v21, 16, v21
	v_add3_u32 v20, v20, v22, s18
	v_and_or_b32 v20, v20, s19, v21
	global_store_dword v[24:25], v20, off
	s_waitcnt vmcnt(20)
	v_lshlrev_b32_e32 v20, 16, v19
	v_and_b32_e32 v19, 0xffff0000, v19
	v_mul_f32_e32 v21, v19, v19
	v_fmac_f32_e32 v21, v20, v20
	s_nop 1
	v_add_f32_dpp v21, v21, v21 quad_perm:[1,0,3,2] row_mask:0xf bank_mask:0xf bound_ctrl:1
	s_nop 1
	v_add_f32_dpp v21, v21, v21 quad_perm:[2,3,0,1] row_mask:0xf bank_mask:0xf bound_ctrl:1
	s_nop 1
	v_add_f32_dpp v21, v21, v21 row_half_mirror row_mask:0xf bank_mask:0xf bound_ctrl:1
	s_nop 1
	v_add_f32_dpp v21, v21, v21 row_mirror row_mask:0xf bank_mask:0xf bound_ctrl:1
	ds_swizzle_b32 v22, v21 offset:swizzle(SWAP,16)
	s_waitcnt lgkmcnt(0)
	v_add_f32_e32 v21, v21, v22
	v_mov_b32_e32 v22, v21
	s_nop 1
	v_permlane32_swap_b32_e32 v21, v22
	v_add_f32_e32 v21, v21, v22
	v_fmamk_f32 v21, v21, 0x3c000000, v206
	v_cmp_gt_f32_e32 vcc, s21, v21
	v_mul_f32_e32 v22, 0x4f800000, v21
	s_nop 0
	v_cndmask_b32_e32 v21, v21, v22, vcc
	v_sqrt_f32_e32 v22, v21
	s_nop 0
	v_add_u32_e32 v23, -1, v22
	v_fma_f32 v24, -v23, v22, v21
	v_cmp_ge_f32_e64 s[0:1], 0, v24
	v_add_u32_e32 v24, 1, v22
	s_nop 0
	v_cndmask_b32_e64 v23, v22, v23, s[0:1]
	v_fma_f32 v22, -v24, v22, v21
	v_cmp_lt_f32_e64 s[0:1], 0, v22
	s_nop 1
	v_cndmask_b32_e64 v22, v23, v24, s[0:1]
	v_mul_f32_e32 v23, 0x37800000, v22
	v_cndmask_b32_e32 v22, v22, v23, vcc
	v_cmp_class_f32_e32 vcc, v21, v207
	s_nop 1
	v_cndmask_b32_e32 v21, v22, v21, vcc
	v_div_scale_f32 v22, s[0:1], v21, v21, 1.0
	v_rcp_f32_e32 v23, v22
	s_nop 0
	v_fma_f32 v24, -v22, v23, 1.0
	v_fmac_f32_e32 v23, v24, v23
	v_div_scale_f32 v24, vcc, 1.0, v21, 1.0
	v_mul_f32_e32 v25, v24, v23
	v_fma_f32 v26, -v22, v25, v24
	v_fmac_f32_e32 v25, v26, v23
	v_fma_f32 v22, -v22, v25, v24
	v_div_fmas_f32 v22, v22, v23, v25
	v_div_fixup_f32 v21, v22, v21, 1.0
	s_waitcnt vmcnt(19)
	v_lshlrev_b32_e32 v22, 16, v18
	v_mul_f32_e32 v23, 0xbfb8aa3b, v22
	v_and_b32_e32 v18, 0xffff0000, v18
	v_mul_f32_e32 v20, v21, v20
	v_exp_f32_e32 v23, v23
	v_mul_f32_e32 v19, v21, v19
	v_mul_f32_e32 v21, 0xbfb8aa3b, v18
	v_exp_f32_e32 v21, v21
	v_add_f32_e32 v23, 1.0, v23
	v_rcp_f32_e32 v23, v23
	v_mul_f32_e32 v20, v6, v20
	v_add_f32_e32 v21, 1.0, v21
	v_rcp_f32_e32 v21, v21
	v_mul_f32_e32 v22, v23, v22
	v_mul_f32_e32 v20, v22, v20
	v_mul_f32_e32 v19, v7, v19
	v_mul_f32_e32 v18, v21, v18
	v_mul_f32_e32 v18, v18, v19
	v_bfe_u32 v19, v20, 16, 1
	v_add3_u32 v19, v20, v19, s18
	v_bfe_u32 v20, v18, 16, 1
	v_lshrrev_b32_e32 v19, 16, v19
	v_add3_u32 v18, v18, v20, s18
	v_and_or_b32 v20, v18, s19, v19
	v_add_co_u32_e32 v18, vcc, s17, v8
	s_nop 1
	v_addc_co_u32_e32 v19, vcc, 0, v9, vcc
	global_store_dword v[18:19], v20, off offset:-4096
	s_waitcnt vmcnt(19)
	v_lshlrev_b32_e32 v20, 16, v17
	v_and_b32_e32 v17, 0xffff0000, v17
	v_mul_f32_e32 v21, v17, v17
	v_fmac_f32_e32 v21, v20, v20
	s_nop 1
	v_add_f32_dpp v21, v21, v21 quad_perm:[1,0,3,2] row_mask:0xf bank_mask:0xf bound_ctrl:1
	s_nop 1
	v_add_f32_dpp v21, v21, v21 quad_perm:[2,3,0,1] row_mask:0xf bank_mask:0xf bound_ctrl:1
	s_nop 1
	v_add_f32_dpp v21, v21, v21 row_half_mirror row_mask:0xf bank_mask:0xf bound_ctrl:1
	s_nop 1
	v_add_f32_dpp v21, v21, v21 row_mirror row_mask:0xf bank_mask:0xf bound_ctrl:1
	ds_swizzle_b32 v22, v21 offset:swizzle(SWAP,16)
	s_waitcnt lgkmcnt(0)
	v_add_f32_e32 v21, v21, v22
	v_mov_b32_e32 v22, v21
	s_nop 1
	v_permlane32_swap_b32_e32 v21, v22
	v_add_f32_e32 v21, v21, v22
	v_fmamk_f32 v21, v21, 0x3c000000, v206
	v_cmp_gt_f32_e32 vcc, s21, v21
	v_mul_f32_e32 v22, 0x4f800000, v21
	s_nop 0
	v_cndmask_b32_e32 v21, v21, v22, vcc
	v_sqrt_f32_e32 v22, v21
	s_nop 0
	v_add_u32_e32 v23, -1, v22
	v_fma_f32 v24, -v23, v22, v21
	v_cmp_ge_f32_e64 s[0:1], 0, v24
	v_add_u32_e32 v24, 1, v22
	s_nop 0
	v_cndmask_b32_e64 v23, v22, v23, s[0:1]
	v_fma_f32 v22, -v24, v22, v21
	v_cmp_lt_f32_e64 s[0:1], 0, v22
	s_nop 1
	v_cndmask_b32_e64 v22, v23, v24, s[0:1]
	v_mul_f32_e32 v23, 0x37800000, v22
	v_cndmask_b32_e32 v22, v22, v23, vcc
	v_cmp_class_f32_e32 vcc, v21, v207
	s_nop 1
	v_cndmask_b32_e32 v21, v22, v21, vcc
	v_div_scale_f32 v22, s[0:1], v21, v21, 1.0
	v_rcp_f32_e32 v23, v22
	s_nop 0
	v_fma_f32 v24, -v22, v23, 1.0
	v_fmac_f32_e32 v23, v24, v23
	v_div_scale_f32 v24, vcc, 1.0, v21, 1.0
	v_mul_f32_e32 v25, v24, v23
	v_fma_f32 v26, -v22, v25, v24
	v_fmac_f32_e32 v25, v26, v23
	v_fma_f32 v22, -v22, v25, v24
	v_div_fmas_f32 v22, v22, v23, v25
	v_div_fixup_f32 v21, v22, v21, 1.0
	s_waitcnt vmcnt(18)
	v_lshlrev_b32_e32 v22, 16, v16
	v_mul_f32_e32 v23, 0xbfb8aa3b, v22
	v_and_b32_e32 v16, 0xffff0000, v16
	v_mul_f32_e32 v20, v21, v20
	v_exp_f32_e32 v23, v23
	v_mul_f32_e32 v17, v21, v17
	v_mul_f32_e32 v21, 0xbfb8aa3b, v16
	v_exp_f32_e32 v21, v21
	v_add_f32_e32 v23, 1.0, v23
	v_rcp_f32_e32 v23, v23
	v_mul_f32_e32 v20, v6, v20
	v_add_f32_e32 v21, 1.0, v21
	v_rcp_f32_e32 v21, v21
	v_mul_f32_e32 v22, v23, v22
	v_mul_f32_e32 v20, v22, v20
	v_mul_f32_e32 v17, v7, v17
	v_mul_f32_e32 v16, v21, v16
	v_mul_f32_e32 v16, v16, v17
	v_bfe_u32 v17, v20, 16, 1
	v_add3_u32 v17, v20, v17, s18
	v_bfe_u32 v20, v16, 16, 1
	v_lshrrev_b32_e32 v17, 16, v17
	v_add3_u32 v16, v16, v20, s18
	v_and_or_b32 v16, v16, s19, v17
	global_store_dword v[18:19], v16, off
	s_waitcnt vmcnt(18)
	v_lshlrev_b32_e32 v16, 16, v15
	v_and_b32_e32 v15, 0xffff0000, v15
	v_mul_f32_e32 v17, v15, v15
	v_fmac_f32_e32 v17, v16, v16
	s_nop 1
	v_add_f32_dpp v17, v17, v17 quad_perm:[1,0,3,2] row_mask:0xf bank_mask:0xf bound_ctrl:1
	s_nop 1
	v_add_f32_dpp v17, v17, v17 quad_perm:[2,3,0,1] row_mask:0xf bank_mask:0xf bound_ctrl:1
	s_nop 1
	v_add_f32_dpp v17, v17, v17 row_half_mirror row_mask:0xf bank_mask:0xf bound_ctrl:1
	s_nop 1
	v_add_f32_dpp v17, v17, v17 row_mirror row_mask:0xf bank_mask:0xf bound_ctrl:1
	ds_swizzle_b32 v18, v17 offset:swizzle(SWAP,16)
	s_waitcnt lgkmcnt(0)
	v_add_f32_e32 v17, v17, v18
	v_mov_b32_e32 v18, v17
	s_nop 1
	v_permlane32_swap_b32_e32 v17, v18
	v_add_f32_e32 v17, v17, v18
	v_fmamk_f32 v17, v17, 0x3c000000, v206
	v_cmp_gt_f32_e32 vcc, s21, v17
	v_mul_f32_e32 v18, 0x4f800000, v17
	s_nop 0
	v_cndmask_b32_e32 v17, v17, v18, vcc
	v_sqrt_f32_e32 v18, v17
	s_nop 0
	v_add_u32_e32 v19, -1, v18
	v_fma_f32 v20, -v19, v18, v17
	v_cmp_ge_f32_e64 s[0:1], 0, v20
	v_add_u32_e32 v20, 1, v18
	s_nop 0
	v_cndmask_b32_e64 v19, v18, v19, s[0:1]
	v_fma_f32 v18, -v20, v18, v17
	v_cmp_lt_f32_e64 s[0:1], 0, v18
	s_nop 1
	v_cndmask_b32_e64 v18, v19, v20, s[0:1]
	v_mul_f32_e32 v19, 0x37800000, v18
	v_cndmask_b32_e32 v18, v18, v19, vcc
	v_cmp_class_f32_e32 vcc, v17, v207
	s_nop 1
	v_cndmask_b32_e32 v17, v18, v17, vcc
	v_div_scale_f32 v18, s[0:1], v17, v17, 1.0
	v_rcp_f32_e32 v19, v18
	s_mov_b32 s0, 0xe000
	v_fma_f32 v20, -v18, v19, 1.0
	v_fmac_f32_e32 v19, v20, v19
	v_div_scale_f32 v20, vcc, 1.0, v17, 1.0
	v_mul_f32_e32 v21, v20, v19
	v_fma_f32 v22, -v18, v21, v20
	v_fmac_f32_e32 v21, v22, v19
	v_fma_f32 v18, -v18, v21, v20
	v_div_fmas_f32 v18, v18, v19, v21
	v_div_fixup_f32 v17, v18, v17, 1.0
	s_waitcnt vmcnt(17)
	v_lshlrev_b32_e32 v18, 16, v14
	v_mul_f32_e32 v19, 0xbfb8aa3b, v18
	v_and_b32_e32 v14, 0xffff0000, v14
	v_mul_f32_e32 v16, v17, v16
	v_exp_f32_e32 v19, v19
	v_mul_f32_e32 v15, v17, v15
	v_mul_f32_e32 v17, 0xbfb8aa3b, v14
	v_exp_f32_e32 v17, v17
	v_add_f32_e32 v19, 1.0, v19
	v_rcp_f32_e32 v19, v19
	v_mul_f32_e32 v16, v6, v16
	v_add_f32_e32 v17, 1.0, v17
	v_rcp_f32_e32 v17, v17
	v_mul_f32_e32 v18, v19, v18
	v_mul_f32_e32 v16, v18, v16
	v_mul_f32_e32 v15, v7, v15
	v_mul_f32_e32 v14, v17, v14
	v_mul_f32_e32 v14, v14, v15
	v_bfe_u32 v15, v16, 16, 1
	v_add3_u32 v15, v16, v15, s18
	v_bfe_u32 v16, v14, 16, 1
	v_lshrrev_b32_e32 v15, 16, v15
	v_add3_u32 v14, v14, v16, s18
	v_and_or_b32 v16, v14, s19, v15
	v_add_co_u32_e32 v14, vcc, s0, v8
	s_nop 1
	v_addc_co_u32_e32 v15, vcc, 0, v9, vcc
	global_store_dword v[14:15], v16, off offset:-4096
	s_waitcnt vmcnt(17)
	v_lshlrev_b32_e32 v16, 16, v13
	v_and_b32_e32 v13, 0xffff0000, v13
	v_mul_f32_e32 v17, v13, v13
	v_fmac_f32_e32 v17, v16, v16
	s_nop 1
	v_add_f32_dpp v17, v17, v17 quad_perm:[1,0,3,2] row_mask:0xf bank_mask:0xf bound_ctrl:1
	s_nop 1
	v_add_f32_dpp v17, v17, v17 quad_perm:[2,3,0,1] row_mask:0xf bank_mask:0xf bound_ctrl:1
	s_nop 1
	v_add_f32_dpp v17, v17, v17 row_half_mirror row_mask:0xf bank_mask:0xf bound_ctrl:1
	s_nop 1
	v_add_f32_dpp v17, v17, v17 row_mirror row_mask:0xf bank_mask:0xf bound_ctrl:1
	ds_swizzle_b32 v18, v17 offset:swizzle(SWAP,16)
	s_waitcnt lgkmcnt(0)
	v_add_f32_e32 v17, v17, v18
	v_mov_b32_e32 v18, v17
	s_nop 1
	v_permlane32_swap_b32_e32 v17, v18
	v_add_f32_e32 v17, v17, v18
	v_fmamk_f32 v17, v17, 0x3c000000, v206
	v_cmp_gt_f32_e32 vcc, s21, v17
	v_mul_f32_e32 v18, 0x4f800000, v17
	s_nop 0
	v_cndmask_b32_e32 v17, v17, v18, vcc
	v_sqrt_f32_e32 v18, v17
	s_nop 0
	v_add_u32_e32 v19, -1, v18
	v_fma_f32 v20, -v19, v18, v17
	v_cmp_ge_f32_e64 s[0:1], 0, v20
	v_add_u32_e32 v20, 1, v18
	s_nop 0
	v_cndmask_b32_e64 v19, v18, v19, s[0:1]
	v_fma_f32 v18, -v20, v18, v17
	v_cmp_lt_f32_e64 s[0:1], 0, v18
	s_nop 1
	v_cndmask_b32_e64 v18, v19, v20, s[0:1]
	v_mul_f32_e32 v19, 0x37800000, v18
	v_cndmask_b32_e32 v18, v18, v19, vcc
	v_cmp_class_f32_e32 vcc, v17, v207
	s_nop 1
	v_cndmask_b32_e32 v17, v18, v17, vcc
	v_div_scale_f32 v18, s[0:1], v17, v17, 1.0
	v_rcp_f32_e32 v19, v18
	s_nop 0
	v_fma_f32 v20, -v18, v19, 1.0
	v_fmac_f32_e32 v19, v20, v19
	v_div_scale_f32 v20, vcc, 1.0, v17, 1.0
	v_mul_f32_e32 v21, v20, v19
	v_fma_f32 v22, -v18, v21, v20
	v_fmac_f32_e32 v21, v22, v19
	v_fma_f32 v18, -v18, v21, v20
	v_div_fmas_f32 v18, v18, v19, v21
	v_div_fixup_f32 v17, v18, v17, 1.0
	s_waitcnt vmcnt(16)
	v_lshlrev_b32_e32 v18, 16, v12
	v_mul_f32_e32 v19, 0xbfb8aa3b, v18
	v_and_b32_e32 v12, 0xffff0000, v12
	v_mul_f32_e32 v16, v17, v16
	v_exp_f32_e32 v19, v19
	v_mul_f32_e32 v13, v17, v13
	v_mul_f32_e32 v17, 0xbfb8aa3b, v12
	v_exp_f32_e32 v17, v17
	v_add_f32_e32 v19, 1.0, v19
	v_rcp_f32_e32 v19, v19
	v_mul_f32_e32 v16, v6, v16
	v_add_f32_e32 v17, 1.0, v17
	v_rcp_f32_e32 v17, v17
	v_mul_f32_e32 v18, v19, v18
	v_mul_f32_e32 v16, v18, v16
	v_mul_f32_e32 v13, v7, v13
	v_mul_f32_e32 v12, v17, v12
	v_mul_f32_e32 v12, v12, v13
	v_bfe_u32 v13, v16, 16, 1
	v_add3_u32 v13, v16, v13, s18
	v_bfe_u32 v16, v12, 16, 1
	v_lshrrev_b32_e32 v13, 16, v13
	v_add3_u32 v12, v12, v16, s18
	v_and_or_b32 v12, v12, s19, v13
	global_store_dword v[14:15], v12, off
	s_waitcnt vmcnt(16)
	v_lshlrev_b32_e32 v12, 16, v11
	v_and_b32_e32 v11, 0xffff0000, v11
	v_mul_f32_e32 v13, v11, v11
	v_fmac_f32_e32 v13, v12, v12
	s_nop 1
	v_add_f32_dpp v13, v13, v13 quad_perm:[1,0,3,2] row_mask:0xf bank_mask:0xf bound_ctrl:1
	s_nop 1
	v_add_f32_dpp v13, v13, v13 quad_perm:[2,3,0,1] row_mask:0xf bank_mask:0xf bound_ctrl:1
	s_nop 1
	v_add_f32_dpp v13, v13, v13 row_half_mirror row_mask:0xf bank_mask:0xf bound_ctrl:1
	s_nop 1
	v_add_f32_dpp v13, v13, v13 row_mirror row_mask:0xf bank_mask:0xf bound_ctrl:1
	ds_swizzle_b32 v14, v13 offset:swizzle(SWAP,16)
	s_waitcnt lgkmcnt(0)
	v_add_f32_e32 v13, v13, v14
	v_mov_b32_e32 v14, v13
	s_nop 1
	v_permlane32_swap_b32_e32 v13, v14
	v_add_f32_e32 v13, v13, v14
	v_fmamk_f32 v13, v13, 0x3c000000, v206
	v_cmp_gt_f32_e32 vcc, s21, v13
	v_mul_f32_e32 v14, 0x4f800000, v13
	s_nop 0
	v_cndmask_b32_e32 v13, v13, v14, vcc
	v_sqrt_f32_e32 v14, v13
	s_nop 0
	v_add_u32_e32 v15, -1, v14
	v_fma_f32 v16, -v15, v14, v13
	v_cmp_ge_f32_e64 s[0:1], 0, v16
	v_add_u32_e32 v16, 1, v14
	s_nop 0
	v_cndmask_b32_e64 v15, v14, v15, s[0:1]
	v_fma_f32 v14, -v16, v14, v13
	v_cmp_lt_f32_e64 s[0:1], 0, v14
	s_nop 1
	v_cndmask_b32_e64 v14, v15, v16, s[0:1]
	v_mul_f32_e32 v15, 0x37800000, v14
	v_cndmask_b32_e32 v14, v14, v15, vcc
	v_cmp_class_f32_e32 vcc, v13, v207
	s_nop 1
	v_cndmask_b32_e32 v13, v14, v13, vcc
	v_div_scale_f32 v14, s[0:1], v13, v13, 1.0
	v_rcp_f32_e32 v15, v14
	s_nop 0
	v_fma_f32 v16, -v14, v15, 1.0
	v_fmac_f32_e32 v15, v16, v15
	v_div_scale_f32 v16, vcc, 1.0, v13, 1.0
	v_mul_f32_e32 v17, v16, v15
	v_fma_f32 v18, -v14, v17, v16
	v_fmac_f32_e32 v17, v18, v15
	v_fma_f32 v14, -v14, v17, v16
	v_div_fmas_f32 v14, v14, v15, v17
	v_div_fixup_f32 v13, v14, v13, 1.0
	s_waitcnt vmcnt(15)
	v_lshlrev_b32_e32 v14, 16, v10
	v_mul_f32_e32 v15, 0xbfb8aa3b, v14
	v_and_b32_e32 v10, 0xffff0000, v10
	v_mul_f32_e32 v12, v13, v12
	v_exp_f32_e32 v15, v15
	v_mul_f32_e32 v11, v13, v11
	v_mul_f32_e32 v13, 0xbfb8aa3b, v10
	v_exp_f32_e32 v13, v13
	v_add_f32_e32 v15, 1.0, v15
	v_rcp_f32_e32 v15, v15
	v_mul_f32_e32 v12, v6, v12
	v_add_f32_e32 v13, 1.0, v13
	v_rcp_f32_e32 v13, v13
	v_mul_f32_e32 v14, v15, v14
	v_mul_f32_e32 v12, v14, v12
	v_mul_f32_e32 v11, v7, v11
	v_mul_f32_e32 v10, v13, v10
	v_mul_f32_e32 v10, v10, v11
	v_bfe_u32 v11, v12, 16, 1
	v_add3_u32 v11, v12, v11, s18
	v_bfe_u32 v12, v10, 16, 1
	v_lshrrev_b32_e32 v11, 16, v11
	v_add3_u32 v10, v10, v12, s18
	v_add_co_u32_e32 v8, vcc, 0xf000, v8
	v_and_or_b32 v10, v10, s19, v11
	s_nop 0
	v_addc_co_u32_e32 v9, vcc, 0, v9, vcc
	global_store_dword v[8:9], v10, off
	s_cbranch_scc1 .Lmy_m3_loop
	s_waitcnt vmcnt(0)

.LBB0_1312:
	v_readlane_b32 s0, v252, 61
	v_readlane_b32 s1, v252, 62
	s_andn2_b64 vcc, exec, s[0:1]
	s_branch .LBB0_1369
	v_readlane_b32 s8, v252, 63
	v_readlane_b32 s9, v253, 0
	s_mov_b64 s[2:3], s[54:55]
	s_mov_b64 s[4:5], s[54:55]
	s_mov_b64 s[6:7], s[54:55]
	s_mov_b64 s[0:1], s[44:45]
	s_andn2_b64 vcc, exec, s[8:9]
	s_mov_b32 s14, 0x8000
	s_movk_i32 s15, 0x6000
	s_movk_i32 s16, 0x4000
	s_mov_b32 s17, 0xc000
	s_movk_i32 s18, 0x7fff
	s_mov_b32 s19, 0xffff0000
	s_movk_i32 s20, 0x2000
	s_mov_b32 s21, 0xf800000
	s_mov_b32 s22, 0xe801000
	s_mov_b64 s[24:25], 0xc00
	v_mbcnt_lo_u32_b32 v0, -1, 0
	v_mbcnt_hi_u32_b32 v0, -1, v0
	s_cbranch_vccnz .LBB0_1316
	v_lshlrev_b32_e32 v6, 1, v0
	v_ashrrev_i32_e32 v7, 31, v6
	v_lshlrev_b64 v[0:1], 1, v[6:7]
	v_lshl_add_u64 v[2:3], s[4:5], 0, v[0:1]
	s_mov_b64 s[4:5], 0x33800000
	v_lshl_add_u64 v[2:3], v[2:3], 0, s[4:5]
	v_lshl_add_u64 v[4:5], s[6:7], 0, v[0:1]
	s_mov_b64 s[4:5], 0x6800000
	s_load_dwordx2 s[0:1], s[0:1], 0x38
	v_lshl_add_u64 v[4:5], v[4:5], 0, s[4:5]
	v_readlane_b32 s4, v251, 39
	v_readlane_b32 s5, v251, 40
	s_mov_b32 s6, s4
	s_ashr_i32 s7, s4, 31
	v_writelane_b32 v251, s4, 39
	s_mov_b32 s8, s58
	s_nop 0
	v_writelane_b32 v251, s5, 40
	s_lshl_b64 s[4:5], s[6:7], 9
	s_waitcnt lgkmcnt(0)
	s_add_u32 s0, s0, s4
	s_addc_u32 s1, s1, s5
	v_lshl_add_u64 v[6:7], v[6:7], 2, s[0:1]
	global_load_dwordx2 v[6:7], v[6:7], off
	s_lshl_b32 s6, s58, 7
	s_lshl_b32 s7, s78, 7
